# saddr LRU variant plus removal of the two dead per-tile x-address computations left over after the x gathers were dropped
# baseline (speedup 1.0000x reference)
; #define LAS __attribute__((address_space(3)))
; __device__ __forceinline__ void lru_fused(const bf16* XC, const bf16* Wrg_t, const bf16* PROJ, bf16* YL, const float* b_a, const float* b_x, const float* sp8,
;                                           LAS unsigned char* lds, int tid, int lane, int wave, int vcu, int G) {
;     ...
;                 for (int kb = 0; kb < 8; ++kb) {
;                     if (kb + 1 < 8) {
; #pragma unroll
;                         for (int cb = 0; cb < 4; ++cb) bq[(kb + 1) & 1][cb] = *(const LAS bf16x8*)(bl + cb * 16 * RG_PITCH + (kb + 1) * 64); }
;                     __builtin_amdgcn_sched_barrier(0);
; #pragma unroll
;                     for (int cb = 0; cb < 4; ++cb)
; #pragma unroll
;                         for (int r2 = 0; r2 < 2; ++r2) acc[r2][cb] = __builtin_amdgcn_mfma_f32_16x16x32_bf16(bq[kb & 1][cb], af[r2][kb], acc[r2][cb], 0, 0, 0);
;                     __builtin_amdgcn_sched_barrier(0);
;                 }
.Lxq_done:
	s_waitcnt lgkmcnt(7)
	v_mfma_f32_16x16x32_bf16 v[142:145], v[86:89], v[70:73], 0
	v_mfma_f32_16x16x32_bf16 v[86:89], v[86:89], v[82:85], 0
	s_waitcnt lgkmcnt(5)
	v_mfma_f32_16x16x32_bf16 v[148:151], v[94:97], v[70:73], 0
	v_mfma_f32_16x16x32_bf16 v[94:97], v[94:97], v[82:85], 0
	s_waitcnt lgkmcnt(3)
	v_mfma_f32_16x16x32_bf16 v[182:185], v[106:109], v[70:73], 0
	v_mfma_f32_16x16x32_bf16 v[106:109], v[106:109], v[82:85], 0
	s_waitcnt lgkmcnt(1)
	v_mfma_f32_16x16x32_bf16 v[70:73], v[160:163], v[70:73], 0
	v_mfma_f32_16x16x32_bf16 v[82:85], v[160:163], v[82:85], 0
	ds_read_b128 v[160:163], v170 offset:128
	ds_read_b128 v[186:189], v170 offset:2304
	ds_read_b128 v[190:193], v170 offset:17536
	ds_read_b128 v[194:197], v170 offset:19712
	v_mfma_f32_16x16x32_bf16 v[142:145], v[90:93], v[62:65], v[142:145]
	v_mfma_f32_16x16x32_bf16 v[86:89], v[90:93], v[78:81], v[86:89]
	v_mfma_f32_16x16x32_bf16 v[90:93], v[98:101], v[62:65], v[148:151]
	v_mfma_f32_16x16x32_bf16 v[94:97], v[98:101], v[78:81], v[94:97]
	v_mfma_f32_16x16x32_bf16 v[98:101], v[154:157], v[62:65], v[182:185]
	s_waitcnt lgkmcnt(4)
	v_mfma_f32_16x16x32_bf16 v[62:65], v[174:177], v[62:65], v[70:73]
	v_mfma_f32_16x16x32_bf16 v[70:73], v[174:177], v[78:81], v[82:85]
	v_mfma_f32_16x16x32_bf16 v[106:109], v[154:157], v[78:81], v[106:109]
	ds_read_b128 v[78:81], v170 offset:192
	s_nop 0
	ds_read_b128 v[82:85], v170 offset:2368
	ds_read_b128 v[148:151], v170 offset:17600
	ds_read_b128 v[154:157], v170 offset:19776
	s_waitcnt lgkmcnt(7)
	v_mfma_f32_16x16x32_bf16 v[142:145], v[160:163], v[54:57], v[142:145]
	v_mfma_f32_16x16x32_bf16 v[86:89], v[160:163], v[74:77], v[86:89]
	s_waitcnt lgkmcnt(6)
	v_mfma_f32_16x16x32_bf16 v[90:93], v[186:189], v[54:57], v[90:93]
	v_mfma_f32_16x16x32_bf16 v[94:97], v[186:189], v[74:77], v[94:97]
	s_waitcnt lgkmcnt(5)
	v_mfma_f32_16x16x32_bf16 v[98:101], v[190:193], v[54:57], v[98:101]
	s_waitcnt lgkmcnt(4)
	v_mfma_f32_16x16x32_bf16 v[54:57], v[194:197], v[54:57], v[62:65]
	v_mfma_f32_16x16x32_bf16 v[62:65], v[194:197], v[74:77], v[70:73]
	v_mfma_f32_16x16x32_bf16 v[106:109], v[190:193], v[74:77], v[106:109]
	s_nop 1
	ds_read_b128 v[70:73], v170 offset:256
	ds_read_b128 v[74:77], v170 offset:2432
	ds_read_b128 v[160:163], v170 offset:17664
	ds_read_b128 v[174:177], v170 offset:19840
	s_waitcnt lgkmcnt(7)
	v_mfma_f32_16x16x32_bf16 v[142:145], v[78:81], v[46:49], v[142:145]
	v_mfma_f32_16x16x32_bf16 v[78:81], v[78:81], v[66:69], v[86:89]
	s_waitcnt lgkmcnt(6)
	v_mfma_f32_16x16x32_bf16 v[86:89], v[82:85], v[46:49], v[90:93]
	v_mfma_f32_16x16x32_bf16 v[82:85], v[82:85], v[66:69], v[94:97]
	s_waitcnt lgkmcnt(5)
	v_mfma_f32_16x16x32_bf16 v[90:93], v[148:151], v[46:49], v[98:101]
	v_mfma_f32_16x16x32_bf16 v[94:97], v[148:151], v[66:69], v[106:109]
	s_waitcnt lgkmcnt(4)
	v_mfma_f32_16x16x32_bf16 v[46:49], v[154:157], v[46:49], v[54:57]
	v_mfma_f32_16x16x32_bf16 v[54:57], v[154:157], v[66:69], v[62:65]
	s_nop 2
	ds_read_b128 v[62:65], v170 offset:320
	ds_read_b128 v[66:69], v170 offset:2496
	ds_read_b128 v[98:101], v170 offset:17728
	ds_read_b128 v[106:109], v170 offset:19904
	s_waitcnt lgkmcnt(7)
	v_mfma_f32_16x16x32_bf16 v[142:145], v[70:73], v[34:37], v[142:145]
	v_mfma_f32_16x16x32_bf16 v[70:73], v[70:73], v[58:61], v[78:81]
	s_waitcnt lgkmcnt(6)
	v_mfma_f32_16x16x32_bf16 v[78:81], v[74:77], v[34:37], v[86:89]
	v_mfma_f32_16x16x32_bf16 v[74:77], v[74:77], v[58:61], v[82:85]
	s_waitcnt lgkmcnt(5)
	v_mfma_f32_16x16x32_bf16 v[82:85], v[160:163], v[34:37], v[90:93]
	v_mfma_f32_16x16x32_bf16 v[86:89], v[160:163], v[58:61], v[94:97]
	s_waitcnt lgkmcnt(4)
	v_mfma_f32_16x16x32_bf16 v[34:37], v[174:177], v[34:37], v[46:49]
	v_mfma_f32_16x16x32_bf16 v[46:49], v[174:177], v[58:61], v[54:57]
	s_nop 2
	ds_read_b128 v[54:57], v170 offset:384
	ds_read_b128 v[58:61], v170 offset:2560
	ds_read_b128 v[90:93], v170 offset:17792
	ds_read_b128 v[94:97], v170 offset:19968
	s_waitcnt lgkmcnt(7)
	v_mfma_f32_16x16x32_bf16 v[142:145], v[62:65], v[30:33], v[142:145]
	v_mfma_f32_16x16x32_bf16 v[62:65], v[62:65], v[50:53], v[70:73]
	s_waitcnt lgkmcnt(6)
	v_mfma_f32_16x16x32_bf16 v[70:73], v[66:69], v[30:33], v[78:81]
	v_mfma_f32_16x16x32_bf16 v[66:69], v[66:69], v[50:53], v[74:77]
	s_waitcnt lgkmcnt(5)
	v_mfma_f32_16x16x32_bf16 v[74:77], v[98:101], v[30:33], v[82:85]
	v_mfma_f32_16x16x32_bf16 v[78:81], v[98:101], v[50:53], v[86:89]
	s_waitcnt lgkmcnt(4)
	v_mfma_f32_16x16x32_bf16 v[30:33], v[106:109], v[30:33], v[34:37]
	v_mfma_f32_16x16x32_bf16 v[34:37], v[106:109], v[50:53], v[46:49]
	s_nop 2
	ds_read_b128 v[46:49], v170 offset:448
	ds_read_b128 v[50:53], v170 offset:2624
	ds_read_b128 v[82:85], v170 offset:17856
	ds_read_b128 v[86:89], v170 offset:20032
	s_waitcnt lgkmcnt(7)
	v_mfma_f32_16x16x32_bf16 v[98:101], v[54:57], v[26:29], v[142:145]
	v_mfma_f32_16x16x32_bf16 v[54:57], v[54:57], v[42:45], v[62:65]
	s_waitcnt lgkmcnt(6)
	v_mfma_f32_16x16x32_bf16 v[62:65], v[58:61], v[26:29], v[70:73]
	v_mfma_f32_16x16x32_bf16 v[58:61], v[58:61], v[42:45], v[66:69]
	s_waitcnt lgkmcnt(5)
	v_mfma_f32_16x16x32_bf16 v[66:69], v[90:93], v[26:29], v[74:77]
	v_mfma_f32_16x16x32_bf16 v[70:73], v[90:93], v[42:45], v[78:81]
	s_waitcnt lgkmcnt(4)
	v_mfma_f32_16x16x32_bf16 v[26:29], v[94:97], v[26:29], v[30:33]
	v_mfma_f32_16x16x32_bf16 v[30:33], v[94:97], v[42:45], v[34:37]
	s_waitcnt lgkmcnt(3)
	v_mfma_f32_16x16x32_bf16 v[106:109], v[46:49], v[22:25], v[98:101]
	v_mfma_f32_16x16x32_bf16 v[98:101], v[46:49], v[38:41], v[54:57]
	s_waitcnt lgkmcnt(2)
	v_mfma_f32_16x16x32_bf16 v[188:191], v[50:53], v[22:25], v[62:65]
	v_mfma_f32_16x16x32_bf16 v[90:93], v[50:53], v[38:41], v[58:61]
	s_waitcnt lgkmcnt(1)
; __device__ __forceinline__ float bf_lo(unsigned w) { return __uint_as_float(w << 16); }
; __device__ __forceinline__ float bf_hi(unsigned w) { return __uint_as_float(w & 0xffff0000u); }
; __device__ __forceinline__ float sigmoidf_(float x) { return fast_rcp(1.0f + fast_exp(-x)); }
; __device__ __forceinline__ void lru_fused(const bf16* XC, const bf16* Wrg_t, const bf16* PROJ, bf16* YL, const float* b_a, const float* b_x, const float* sp8,
;                                           LAS unsigned char* lds, int tid, int lane, int wave, int vcu, int G) {
;     ...
;             { const size_t rown = (i + 1 < SEQ / 256) ? row0 + 256 : row0;
; #pragma unroll
;                 for (int r2 = 0; r2 < 2; ++r2) { const size_t ro = (rown + 16 * r2 + fr) * D, rg = (rown + 16 * r2 + fr) * NIN;
; #pragma unroll
;                     for (int kb = 0; kb < 8; ++kb) af[r2][kb] = *(const bf16x8*)(abase + ro + 32 * kb);
; #pragma unroll
;                     for (int c2 = 0; c2 < 2; ++c2) { xqn[r2][c2] = *(const v2u*)(xbase + ro + 16 * c2); gqn[r2][c2] = *(const v2u*)(gbase + rg + 16 * c2); } } }
;             float A[2][2][4], U[2][2][4];
; #pragma unroll
;             for (int r2 = 0; r2 < 2; ++r2)
; #pragma unroll
;                 for (int c2 = 0; c2 < 2; ++c2) { const f32x4 rp = acc[r2][c2] + ba[c2], ip = acc[r2][c2 + 2] + bx[c2]; const v2u xw = xq[r2][c2];
;                     const float xv[4] = {bf_lo(xw.x), bf_hi(xw.x), bf_lo(xw.y), bf_hi(xw.y)};
; #pragma unroll
;                     for (int j = 0; j < 4; ++j) { const float r = pg8::sigmoidf_(rp[j]), ig = pg8::sigmoidf_(ip[j]);
;                         const float av = __builtin_amdgcn_exp2f(sp[c2][j] * r);
;                         A[r2][c2][j] = av; U[r2][c2][j] = __builtin_amdgcn_sqrtf(fmaxf(__builtin_fmaf(-av, av, 1.0f), 0.0f)) * (ig * xv[j]); } }
	v_mfma_f32_16x16x32_bf16 v[182:185], v[82:85], v[22:25], v[66:69]
	v_mfma_f32_16x16x32_bf16 v[94:97], v[82:85], v[38:41], v[70:73]
	s_waitcnt lgkmcnt(0)
	v_mfma_f32_16x16x32_bf16 v[192:195], v[86:89], v[22:25], v[26:29]
	v_mfma_f32_16x16x32_bf16 v[86:89], v[86:89], v[38:41], v[30:33]
	v_add_f32_e32 v3, v6, v106
	v_mul_f32_e32 v3, 0xbfb8aa3b, v3
	v_exp_f32_e32 v3, v3
	s_add_u32 s23, s19, 0xffffff00
	s_addc_u32 s24, s20, -1
	s_cmp_eq_u32 s64, 0x3e00000
	s_cselect_b32 s25, s24, s20
	s_cselect_b32 s24, s23, s19
	v_mov_b32_e32 v39, s25
	v_or_b32_e32 v38, s24, v110
	v_lshlrev_b64 v[40:41], 13, v[38:39]
	v_mad_u64_u32 v[38:39], s[26:27], v38, s13, v[126:127]
	s_mul_i32 s23, s25, 0xa000
	v_lshl_add_u64 v[22:23], v[122:123], 0, v[40:41]
	v_subrev_u32_e32 v22, s68, v22
	v_add_u32_e32 v39, s23, v39
	global_load_dwordx4 v[70:73], v22, s[68:69]
	s_nop 0
	v_add_f32_e32 v173, v14, v182
	v_mul_f32_e32 v173, 0xbfb8aa3b, v173
	v_exp_f32_e32 v174, v173
	v_add_f32_e32 v3, 1.0, v3
	v_rcp_f32_e32 v3, v3
	v_add_f32_e32 v107, v7, v107
	v_add_f32_e32 v174, 1.0, v174
	v_mul_f32_e32 v107, 0xbfb8aa3b, v107
	v_mul_f32_e32 v3, v134, v3
	v_exp_f32_e32 v173, v3
	v_rcp_f32_e32 v174, v174
	v_exp_f32_e32 v107, v107
	v_lshlrev_b32_e32 v106, 16, v198
	v_fma_f32 v175, -v173, v173, 1.0
	global_load_dwordx4 v[62:65], v22, s[68:69] offset:64
	v_mul_f32_e32 v106, v174, v106
	v_add_f32_e32 v174, v15, v183
	v_add_f32_e32 v107, 1.0, v107
	v_max_f32_e32 v175, 0, v175
	v_mul_f32_e32 v174, 0xbfb8aa3b, v174
	v_rcp_f32_e32 v107, v107
	v_sqrt_f32_e32 v175, v175
	v_exp_f32_e32 v174, v174
	v_add_f32_e32 v177, v16, v184
	v_mul_f32_e32 v107, v135, v107
	v_mul_f32_e32 v175, v106, v175
	v_add_f32_e32 v106, 1.0, v174
	v_exp_f32_e32 v174, v107
	v_add_f32_e32 v107, v8, v108
	v_mul_f32_e32 v107, 0xbfb8aa3b, v107
	v_exp_f32_e32 v107, v107
	global_load_dwordx4 v[54:57], v22, s[68:69] offset:128
	v_fma_f32 v108, -v174, v174, 1.0
	v_rcp_f32_e32 v106, v106
	v_max_f32_e32 v108, 0, v108
	v_add_f32_e32 v107, 1.0, v107
	v_mul_f32_e32 v177, 0xbfb8aa3b, v177
	v_rcp_f32_e32 v107, v107
	v_sqrt_f32_e32 v108, v108
	v_exp_f32_e32 v181, v177
	v_and_b32_e32 v176, 0xffff0000, v198
	v_mul_f32_e32 v106, v106, v176
	v_mul_f32_e32 v107, v132, v107
	v_mul_f32_e32 v177, v106, v108
	v_add_f32_e32 v106, 1.0, v181
	v_exp_f32_e32 v181, v107
	v_add_f32_e32 v107, v9, v109
	global_load_dwordx4 v[46:49], v22, s[68:69] offset:192
	v_mul_f32_e32 v107, 0xbfb8aa3b, v107
	v_exp_f32_e32 v107, v107
	v_add_f32_e32 v109, v17, v185
	v_mul_f32_e32 v109, 0xbfb8aa3b, v109
	v_exp_f32_e32 v109, v109
	v_add_f32_e32 v107, 1.0, v107
	v_rcp_f32_e32 v107, v107
	v_fma_f32 v108, -v181, v181, 1.0
	v_max_f32_e32 v108, 0, v108
	v_and_b32_e32 v3, 0xffff0000, v199
	v_mul_f32_e32 v107, v133, v107
	v_exp_f32_e32 v176, v107
	v_sqrt_f32_e32 v107, v108
	v_add_f32_e32 v108, 1.0, v109
	v_rcp_f32_e32 v108, v108
	global_load_dwordx4 v[34:37], v22, s[68:69] offset:256
	v_fma_f32 v109, -v176, v176, 1.0
	v_max_f32_e32 v109, 0, v109
	v_sqrt_f32_e32 v109, v109
	v_mul_f32_e32 v3, v108, v3
	v_add_f32_e32 v108, v18, v192
	v_rcp_f32_e32 v106, v106
	v_mul_f32_e32 v182, v3, v109
	v_add_f32_e32 v3, v10, v188
	v_mul_f32_e32 v3, 0xbfb8aa3b, v3
	v_exp_f32_e32 v3, v3
	v_mul_f32_e32 v108, 0xbfb8aa3b, v108
	v_exp_f32_e32 v108, v108
	v_lshlrev_b32_e32 v186, 16, v199
	v_add_f32_e32 v3, 1.0, v3
	v_rcp_f32_e32 v3, v3
	v_mul_f32_e32 v106, v106, v186
	global_load_dwordx4 v[30:33], v22, s[68:69] offset:320
	v_mul_f32_e32 v184, v106, v107
	v_lshlrev_b32_e32 v107, 16, v105
	v_mul_f32_e32 v3, v138, v3
	v_exp_f32_e32 v183, v3
	v_and_b32_e32 v3, 0xffff0000, v105
	v_add_f32_e32 v105, 1.0, v108
	v_rcp_f32_e32 v105, v105
	v_lshlrev_b32_e32 v106, 16, v104
	v_fma_f32 v108, -v183, v183, 1.0
	v_add_f32_e32 v109, v19, v193
	v_mul_f32_e32 v105, v105, v106
	v_add_f32_e32 v106, v11, v189
	v_mul_f32_e32 v106, 0xbfb8aa3b, v106
	v_exp_f32_e32 v106, v106
	v_max_f32_e32 v108, 0, v108
	global_load_dwordx4 v[26:29], v22, s[68:69] offset:384
	v_mul_f32_e32 v109, 0xbfb8aa3b, v109
	v_sqrt_f32_e32 v108, v108
	v_add_f32_e32 v106, 1.0, v106
	v_rcp_f32_e32 v106, v106
	v_exp_f32_e32 v109, v109
	v_mul_f32_e32 v186, v105, v108
	v_and_b32_e32 v104, 0xffff0000, v104
	v_mul_f32_e32 v106, v139, v106
	v_exp_f32_e32 v185, v106
	v_add_f32_e32 v106, v12, v190
	v_mul_f32_e32 v106, 0xbfb8aa3b, v106
	v_exp_f32_e32 v106, v106
	v_add_f32_e32 v105, 1.0, v109
	v_rcp_f32_e32 v105, v105
	v_fma_f32 v108, -v185, v185, 1.0
	s_nop 0
	global_load_dwordx4 v[22:25], v22, s[68:69] offset:448
	v_add_f32_e32 v106, 1.0, v106
	v_rcp_f32_e32 v106, v106
	v_mul_f32_e32 v104, v105, v104
	v_max_f32_e32 v108, 0, v108
	v_sqrt_f32_e32 v108, v108
	v_mul_f32_e32 v105, v136, v106
	v_exp_f32_e32 v189, v105
	v_add_f32_e32 v105, v13, v191
	v_mul_f32_e32 v105, 0xbfb8aa3b, v105
	v_exp_f32_e32 v105, v105
	v_mul_f32_e32 v188, v104, v108
	v_add_f32_e32 v108, v21, v195
	v_mul_f32_e32 v108, 0xbfb8aa3b, v108
	v_add_f32_e32 v105, 1.0, v105
	v_rcp_f32_e32 v105, v105
	s_nop 0
	v_exp_f32_e32 v108, v108
	v_fma_f32 v106, -v189, v189, 1.0
	v_max_f32_e32 v106, 0, v106
	v_mul_f32_e32 v105, v137, v105
	v_exp_f32_e32 v187, v105
	v_sqrt_f32_e32 v105, v106
	v_add_f32_e32 v106, 1.0, v108
	v_rcp_f32_e32 v106, v106
	v_fma_f32 v108, -v187, v187, 1.0
	v_max_f32_e32 v108, 0, v108
	v_sqrt_f32_e32 v108, v108
	v_mul_f32_e32 v3, v106, v3
	v_add_f32_e32 v109, v20, v194
	v_mul_f32_e32 v109, 0xbfb8aa3b, v109
	v_mul_f32_e32 v190, v3, v108
	v_add_f32_e32 v3, v6, v98
	v_mul_f32_e32 v3, 0xbfb8aa3b, v3
	v_exp_f32_e32 v3, v3
	v_exp_f32_e32 v109, v109
	v_add_f32_e32 v99, v7, v99
	v_mul_f32_e32 v99, 0xbfb8aa3b, v99
	v_add_f32_e32 v3, 1.0, v3
	v_rcp_f32_e32 v3, v3
	v_exp_f32_e32 v99, v99
; __device__ __forceinline__ float bf_lo(unsigned w) { return __uint_as_float(w << 16); }
; __device__ __forceinline__ float bf_hi(unsigned w) { return __uint_as_float(w & 0xffff0000u); }
; __device__ __forceinline__ float sigmoidf_(float x) { return fast_rcp(1.0f + fast_exp(-x)); }
; __device__ __forceinline__ void lru_fused(const bf16* XC, const bf16* Wrg_t, const bf16* PROJ, bf16* YL, const float* b_a, const float* b_x, const float* sp8,
;                                           LAS unsigned char* lds, int tid, int lane, int wave, int vcu, int G) {
;     ...
;             { const size_t rown = (i + 1 < SEQ / 256) ? row0 + 256 : row0;
; #pragma unroll
;                 for (int r2 = 0; r2 < 2; ++r2) { const size_t ro = (rown + 16 * r2 + fr) * D, rg = (rown + 16 * r2 + fr) * NIN;
; #pragma unroll
;                     for (int kb = 0; kb < 8; ++kb) af[r2][kb] = *(const bf16x8*)(abase + ro + 32 * kb);
; #pragma unroll
;                     for (int c2 = 0; c2 < 2; ++c2) { xqn[r2][c2] = *(const v2u*)(xbase + ro + 16 * c2); gqn[r2][c2] = *(const v2u*)(gbase + rg + 16 * c2); } } }
;             float A[2][2][4], U[2][2][4];
; #pragma unroll
;             for (int r2 = 0; r2 < 2; ++r2)
; #pragma unroll
;                 for (int c2 = 0; c2 < 2; ++c2) { const f32x4 rp = acc[r2][c2] + ba[c2], ip = acc[r2][c2 + 2] + bx[c2]; const v2u xw = xq[r2][c2];
;                     const float xv[4] = {bf_lo(xw.x), bf_hi(xw.x), bf_lo(xw.y), bf_hi(xw.y)};
; #pragma unroll
;                     for (int j = 0; j < 4; ++j) { const float r = pg8::sigmoidf_(rp[j]), ig = pg8::sigmoidf_(ip[j]);
;                         const float av = __builtin_amdgcn_exp2f(sp[c2][j] * r);
;                         A[r2][c2][j] = av; U[r2][c2][j] = __builtin_amdgcn_sqrtf(fmaxf(__builtin_fmaf(-av, av, 1.0f), 0.0f)) * (ig * xv[j]); } }
	v_add_f32_e32 v104, 1.0, v109
	v_add_f32_e32 v94, v14, v94
	v_rcp_f32_e32 v104, v104
	v_mul_f32_e32 v94, 0xbfb8aa3b, v94
	v_mul_f32_e32 v3, v134, v3
	v_exp_f32_e32 v94, v94
	v_exp_f32_e32 v98, v3
	global_load_dwordx4 v[154:157], v[38:39], off
	v_add_f32_e32 v99, 1.0, v99
	v_add_f32_e32 v101, v9, v101
	v_rcp_f32_e32 v99, v99
	v_mul_f32_e32 v101, 0xbfb8aa3b, v101
	v_exp_f32_e32 v101, v101
	v_mul_f32_e32 v104, v104, v107
	v_mul_f32_e32 v191, v104, v105
	v_lshlrev_b32_e32 v105, 16, v103
	v_and_b32_e32 v3, 0xffff0000, v103
	v_add_f32_e32 v94, 1.0, v94
	v_fma_f32 v103, -v98, v98, 1.0
	v_add_f32_e32 v95, v15, v95
	v_rcp_f32_e32 v94, v94
	v_max_f32_e32 v103, 0, v103
	v_mul_f32_e32 v95, 0xbfb8aa3b, v95
	v_mul_f32_e32 v99, v135, v99
	v_sqrt_f32_e32 v103, v103
	v_exp_f32_e32 v95, v95
	v_exp_f32_e32 v99, v99
	v_add_f32_e32 v100, v8, v100
	v_add_f32_e32 v101, 1.0, v101
	v_mul_f32_e32 v100, 0xbfb8aa3b, v100
	v_rcp_f32_e32 v101, v101
	v_lshlrev_b32_e32 v104, 16, v102
	v_exp_f32_e32 v100, v100
	v_mul_f32_e32 v94, v94, v104
	v_mul_f32_e32 v94, v94, v103
	v_add_f32_e32 v95, 1.0, v95
	v_fma_f32 v103, -v99, v99, 1.0
	v_add_f32_e32 v97, v17, v97
	v_rcp_f32_e32 v95, v95
	v_lshl_add_u64 v[38:39], v[110:111], 0, s[24:25]
	v_lshl_add_u64 v[148:149], v[38:39], 0, 16
	v_lshlrev_b64 v[150:151], 13, v[148:149]
	v_lshl_add_u64 v[38:39], v[122:123], 0, v[150:151]
	v_subrev_u32_e32 v38, s68, v38
	global_load_dwordx4 v[82:85], v38, s[68:69]
	v_max_f32_e32 v103, 0, v103
	v_mul_f32_e32 v97, 0xbfb8aa3b, v97
	v_mul_f32_e32 v101, v133, v101
	v_sqrt_f32_e32 v103, v103
	v_add_f32_e32 v100, 1.0, v100
	v_exp_f32_e32 v97, v97
	v_exp_f32_e32 v101, v101
	v_rcp_f32_e32 v100, v100
	v_and_b32_e32 v102, 0xffff0000, v102
	v_mul_f32_e32 v95, v95, v102
	v_add_f32_e32 v96, v16, v96
	v_mul_f32_e32 v95, v95, v103
	v_add_f32_e32 v97, 1.0, v97
	v_fma_f32 v103, -v101, v101, 1.0
	v_mul_f32_e32 v96, 0xbfb8aa3b, v96
	global_load_dwordx4 v[78:81], v38, s[68:69] offset:64
	v_mul_f32_e32 v100, v132, v100
	v_rcp_f32_e32 v97, v97
	v_max_f32_e32 v103, 0, v103
	v_exp_f32_e32 v96, v96
	v_exp_f32_e32 v100, v100
	v_sqrt_f32_e32 v103, v103
	v_mul_f32_e32 v3, v97, v3
	v_add_f32_e32 v96, 1.0, v96
	v_fma_f32 v102, -v100, v100, 1.0
	v_mul_f32_e32 v97, v3, v103
	v_add_f32_e32 v3, v10, v90
	v_rcp_f32_e32 v96, v96
	v_max_f32_e32 v102, 0, v102
	v_mul_f32_e32 v3, 0xbfb8aa3b, v3
	v_sqrt_f32_e32 v102, v102
	global_load_dwordx4 v[74:77], v38, s[68:69] offset:128
	v_exp_f32_e32 v3, v3
	v_mul_f32_e32 v96, v96, v105
	v_lshlrev_b32_e32 v90, 16, v4
	v_mul_f32_e32 v96, v96, v102
	v_and_b32_e32 v102, 0xffff0000, v4
	v_add_f32_e32 v3, 1.0, v3
	v_add_f32_e32 v4, v18, v86
	v_rcp_f32_e32 v3, v3
	v_mul_f32_e32 v4, 0xbfb8aa3b, v4
	v_exp_f32_e32 v86, v4
	v_lshlrev_b32_e32 v103, 16, v5
	v_mul_f32_e32 v3, v138, v3
	v_exp_f32_e32 v4, v3
	v_and_b32_e32 v3, 0xffff0000, v5
	v_add_f32_e32 v5, 1.0, v86
	v_rcp_f32_e32 v5, v5
	global_load_dwordx4 v[66:69], v38, s[68:69] offset:192
	v_fma_f32 v86, -v4, v4, 1.0
	v_add_f32_e32 v87, v19, v87
	v_max_f32_e32 v86, 0, v86
	v_mul_f32_e32 v5, v5, v90
	v_add_f32_e32 v90, v11, v91
	v_mul_f32_e32 v90, 0xbfb8aa3b, v90
	v_exp_f32_e32 v90, v90
	v_mul_f32_e32 v87, 0xbfb8aa3b, v87
	v_sqrt_f32_e32 v86, v86
	v_exp_f32_e32 v87, v87
	v_add_f32_e32 v90, 1.0, v90
	v_rcp_f32_e32 v90, v90
	v_mul_f32_e32 v86, v5, v86
	v_add_f32_e32 v5, 1.0, v87
	v_rcp_f32_e32 v87, v5
	global_load_dwordx4 v[58:61], v38, s[68:69] offset:256
	v_mul_f32_e32 v5, v139, v90
	v_add_f32_e32 v90, v12, v92
	v_mul_f32_e32 v90, 0xbfb8aa3b, v90
	v_exp_f32_e32 v90, v90
	v_exp_f32_e32 v5, v5
	v_add_f32_e32 v88, v20, v88
; __device__ __forceinline__ float bf_lo(unsigned w) { return __uint_as_float(w << 16); }
; __device__ __forceinline__ float bf_hi(unsigned w) { return __uint_as_float(w & 0xffff0000u); }
; __device__ __forceinline__ float sigmoidf_(float x) { return fast_rcp(1.0f + fast_exp(-x)); }
; __device__ __forceinline__ void lru_fused(const bf16* XC, const bf16* Wrg_t, const bf16* PROJ, bf16* YL, const float* b_a, const float* b_x, const float* sp8,
;                                           LAS unsigned char* lds, int tid, int lane, int wave, int vcu, int G) {
;     ...
;                 for (int r2 = 0; r2 < 2; ++r2) { const size_t ro = (rown + 16 * r2 + fr) * D, rg = (rown + 16 * r2 + fr) * NIN;
; #pragma unroll
;                     for (int kb = 0; kb < 8; ++kb) af[r2][kb] = *(const bf16x8*)(abase + ro + 32 * kb);
; #pragma unroll
;                     for (int c2 = 0; c2 < 2; ++c2) { xqn[r2][c2] = *(const v2u*)(xbase + ro + 16 * c2); gqn[r2][c2] = *(const v2u*)(gbase + rg + 16 * c2); } } }
;             float A[2][2][4], U[2][2][4];
; #pragma unroll
;             for (int r2 = 0; r2 < 2; ++r2)
; #pragma unroll
;                 for (int c2 = 0; c2 < 2; ++c2) { const f32x4 rp = acc[r2][c2] + ba[c2], ip = acc[r2][c2 + 2] + bx[c2]; const v2u xw = xq[r2][c2];
;                     const float xv[4] = {bf_lo(xw.x), bf_hi(xw.x), bf_lo(xw.y), bf_hi(xw.y)};
; #pragma unroll
;                     for (int j = 0; j < 4; ++j) { const float r = pg8::sigmoidf_(rp[j]), ig = pg8::sigmoidf_(ip[j]);
;                         const float av = __builtin_amdgcn_exp2f(sp[c2][j] * r);
;                         A[r2][c2][j] = av; U[r2][c2][j] = __builtin_amdgcn_sqrtf(fmaxf(__builtin_fmaf(-av, av, 1.0f), 0.0f)) * (ig * xv[j]); } }
;     ...
; #pragma unroll
;             for (int r2 = 0; r2 < 2; ++r2)
; #pragma unroll
;                 for (int c2 = 0; c2 < 2; ++c2)
;                     asm volatile("s_nop 1\n\t" LRU_STEP(1) LRU_STEP(2) LRU_STEP(4) LRU_STEP(8)
;                                  : "+v"(A[r2][c2][0]), "+v"(A[r2][c2][1]), "+v"(A[r2][c2][2]), "+v"(A[r2][c2][3]), "+v"(U[r2][c2][0]), "+v"(U[r2][c2][1]), "+v"(U[r2][c2][2]), "+v"(U[r2][c2][3]));
	v_add_f32_e32 v89, v21, v89
	v_add_f32_e32 v90, 1.0, v90
	v_rcp_f32_e32 v90, v90
	v_fma_f32 v91, -v5, v5, 1.0
	v_max_f32_e32 v91, 0, v91
	v_sqrt_f32_e32 v91, v91
	v_mul_f32_e32 v90, v136, v90
	v_exp_f32_e32 v92, v90
	v_add_f32_e32 v90, v13, v93
	global_load_dwordx4 v[50:53], v38, s[68:69] offset:320
	v_mul_f32_e32 v90, 0xbfb8aa3b, v90
	v_exp_f32_e32 v90, v90
	v_mul_f32_e32 v88, 0xbfb8aa3b, v88
	v_mul_f32_e32 v89, 0xbfb8aa3b, v89
	v_exp_f32_e32 v88, v88
	v_add_f32_e32 v90, 1.0, v90
	v_rcp_f32_e32 v90, v90
	v_exp_f32_e32 v89, v89
	v_mul_f32_e32 v87, v87, v102
	v_mul_f32_e32 v87, v87, v91
	v_mul_f32_e32 v90, v137, v90
	v_exp_f32_e32 v93, v90
	v_fma_f32 v91, -v92, v92, 1.0
	v_max_f32_e32 v91, 0, v91
	v_add_f32_e32 v88, 1.0, v88
	global_load_dwordx4 v[42:45], v38, s[68:69] offset:384
	v_sqrt_f32_e32 v90, v91
	v_add_f32_e32 v89, 1.0, v89
	v_fma_f32 v91, -v93, v93, 1.0
	v_rcp_f32_e32 v88, v88
	v_rcp_f32_e32 v89, v89
	v_max_f32_e32 v91, 0, v91
	v_sqrt_f32_e32 v91, v91
	v_mul_f32_e32 v88, v88, v103
	v_mul_f32_e32 v3, v89, v3
	v_mul_f32_e32 v88, v88, v90
	v_mul_f32_e32 v89, v3, v91
	s_nop 1
	v_fmac_f32_dpp v175, v175, v173 row_shr:1 row_mask:0xf bank_mask:0xf
	v_mul_f32_dpp v173, v173, v173 row_shr:1 row_mask:0xf bank_mask:0xf
	v_fmac_f32_dpp v177, v177, v174 row_shr:1 row_mask:0xf bank_mask:0xf
	v_mul_f32_dpp v174, v174, v174 row_shr:1 row_mask:0xf bank_mask:0xf
	s_nop 0
	global_load_dwordx4 v[38:41], v38, s[68:69] offset:448
	v_fmac_f32_dpp v184, v184, v181 row_shr:1 row_mask:0xf bank_mask:0xf
	v_mul_f32_dpp v181, v181, v181 row_shr:1 row_mask:0xf bank_mask:0xf
	v_fmac_f32_dpp v182, v182, v176 row_shr:1 row_mask:0xf bank_mask:0xf
	v_mul_f32_dpp v176, v176, v176 row_shr:1 row_mask:0xf bank_mask:0xf
	v_fmac_f32_dpp v175, v175, v173 row_shr:2 row_mask:0xf bank_mask:0xf
	v_mul_f32_dpp v173, v173, v173 row_shr:2 row_mask:0xf bank_mask:0xf
	v_fmac_f32_dpp v177, v177, v174 row_shr:2 row_mask:0xf bank_mask:0xf
	v_mul_f32_dpp v174, v174, v174 row_shr:2 row_mask:0xf bank_mask:0xf
	v_fmac_f32_dpp v184, v184, v181 row_shr:2 row_mask:0xf bank_mask:0xf
	v_mul_f32_dpp v181, v181, v181 row_shr:2 row_mask:0xf bank_mask:0xf
	v_fmac_f32_dpp v182, v182, v176 row_shr:2 row_mask:0xf bank_mask:0xf
	v_mul_f32_dpp v176, v176, v176 row_shr:2 row_mask:0xf bank_mask:0xf
	v_fmac_f32_dpp v175, v175, v173 row_shr:4 row_mask:0xf bank_mask:0xf
	v_mul_f32_dpp v173, v173, v173 row_shr:4 row_mask:0xf bank_mask:0xf
	v_fmac_f32_dpp v177, v177, v174 row_shr:4 row_mask:0xf bank_mask:0xf
	v_mad_u64_u32 v[162:163], s[24:25], v148, s13, v[126:127]
	v_mov_b32_e32 v148, v163
	v_mad_u64_u32 v[148:149], s[24:25], v149, s13, v[148:149]
	v_mov_b32_e32 v163, v148
	v_mul_f32_dpp v174, v174, v174 row_shr:4 row_mask:0xf bank_mask:0xf
	v_fmac_f32_dpp v184, v184, v181 row_shr:4 row_mask:0xf bank_mask:0xf
	v_mul_f32_dpp v181, v181, v181 row_shr:4 row_mask:0xf bank_mask:0xf
	v_fmac_f32_dpp v182, v182, v176 row_shr:4 row_mask:0xf bank_mask:0xf
	v_mul_f32_dpp v176, v176, v176 row_shr:4 row_mask:0xf bank_mask:0xf
	v_fmac_f32_dpp v175, v175, v173 row_shr:8 row_mask:0xf bank_mask:0xf
	v_mul_f32_dpp v173, v173, v173 row_shr:8 row_mask:0xf bank_mask:0xf
	v_fmac_f32_dpp v177, v177, v174 row_shr:8 row_mask:0xf bank_mask:0xf
	v_mul_f32_dpp v174, v174, v174 row_shr:8 row_mask:0xf bank_mask:0xf
	v_fmac_f32_dpp v184, v184, v181 row_shr:8 row_mask:0xf bank_mask:0xf
	v_mul_f32_dpp v181, v181, v181 row_shr:8 row_mask:0xf bank_mask:0xf
	v_fmac_f32_dpp v182, v182, v176 row_shr:8 row_mask:0xf bank_mask:0xf
	v_mul_f32_dpp v176, v176, v176 row_shr:8 row_mask:0xf bank_mask:0xf

; __device__ __forceinline__ void lru_fused(const bf16* XC, const bf16* Wrg_t, const bf16* PROJ, bf16* YL, const float* b_a, const float* b_x, const float* sp8,
;                                           LAS unsigned char* lds, int tid, int lane, int wave, int vcu, int G) {
;     ...
; #pragma unroll
;             for (int r2 = 0; r2 < 2; ++r2)
; #pragma unroll
;                 for (int c2 = 0; c2 < 2; ++c2)
;                     asm volatile("s_nop 1\n\t" LRU_STEP(1) LRU_STEP(2) LRU_STEP(4) LRU_STEP(8)
;                                  : "+v"(A[r2][c2][0]), "+v"(A[r2][c2][1]), "+v"(A[r2][c2][2]), "+v"(A[r2][c2][3]), "+v"(U[r2][c2][0]), "+v"(U[r2][c2][1]), "+v"(U[r2][c2][2]), "+v"(U[r2][c2][3]));
;     ...
;             const int l15 = (lane & 48) | 15;
; #pragma unroll
;             for (int c2 = 0; c2 < 2; ++c2)
; #pragma unroll
;                 for (int j = 0; j < 4; ++j) { const float a15 = __shfl(A[0][c2][j], l15), u15 = __shfl(U[0][c2][j], l15);
	ds_bpermute_b32 v90, v172, v173
	ds_bpermute_b32 v102, v172, v175
	s_nop 0
	global_load_dwordx4 v[160:163], v[162:163], off
	ds_bpermute_b32 v103, v172, v177
	ds_bpermute_b32 v91, v172, v174
	ds_bpermute_b32 v104, v172, v184
	ds_bpermute_b32 v105, v172, v182
	s_nop 1
	v_fmac_f32_dpp v186, v186, v183 row_shr:1 row_mask:0xf bank_mask:0xf
	v_mul_f32_dpp v183, v183, v183 row_shr:1 row_mask:0xf bank_mask:0xf
	v_fmac_f32_dpp v188, v188, v185 row_shr:1 row_mask:0xf bank_mask:0xf
	v_mul_f32_dpp v185, v185, v185 row_shr:1 row_mask:0xf bank_mask:0xf
	v_fmac_f32_dpp v191, v191, v189 row_shr:1 row_mask:0xf bank_mask:0xf
	v_mul_f32_dpp v189, v189, v189 row_shr:1 row_mask:0xf bank_mask:0xf
	v_fmac_f32_dpp v190, v190, v187 row_shr:1 row_mask:0xf bank_mask:0xf
	v_mul_f32_dpp v187, v187, v187 row_shr:1 row_mask:0xf bank_mask:0xf
	v_fmac_f32_dpp v186, v186, v183 row_shr:2 row_mask:0xf bank_mask:0xf
	v_mul_f32_dpp v183, v183, v183 row_shr:2 row_mask:0xf bank_mask:0xf
	v_fmac_f32_dpp v188, v188, v185 row_shr:2 row_mask:0xf bank_mask:0xf
	v_mul_f32_dpp v185, v185, v185 row_shr:2 row_mask:0xf bank_mask:0xf
	v_fmac_f32_dpp v191, v191, v189 row_shr:2 row_mask:0xf bank_mask:0xf
	v_mul_f32_dpp v189, v189, v189 row_shr:2 row_mask:0xf bank_mask:0xf
	v_fmac_f32_dpp v190, v190, v187 row_shr:2 row_mask:0xf bank_mask:0xf
	v_mul_f32_dpp v187, v187, v187 row_shr:2 row_mask:0xf bank_mask:0xf
	v_fmac_f32_dpp v186, v186, v183 row_shr:4 row_mask:0xf bank_mask:0xf
	v_mul_f32_dpp v183, v183, v183 row_shr:4 row_mask:0xf bank_mask:0xf
	v_fmac_f32_dpp v188, v188, v185 row_shr:4 row_mask:0xf bank_mask:0xf
	v_mul_f32_dpp v185, v185, v185 row_shr:4 row_mask:0xf bank_mask:0xf
	v_fmac_f32_dpp v191, v191, v189 row_shr:4 row_mask:0xf bank_mask:0xf
	v_mul_f32_dpp v189, v189, v189 row_shr:4 row_mask:0xf bank_mask:0xf
	v_fmac_f32_dpp v190, v190, v187 row_shr:4 row_mask:0xf bank_mask:0xf
	v_mul_f32_dpp v187, v187, v187 row_shr:4 row_mask:0xf bank_mask:0xf
	v_fmac_f32_dpp v186, v186, v183 row_shr:8 row_mask:0xf bank_mask:0xf
	v_mul_f32_dpp v183, v183, v183 row_shr:8 row_mask:0xf bank_mask:0xf
	v_fmac_f32_dpp v188, v188, v185 row_shr:8 row_mask:0xf bank_mask:0xf
	v_mul_f32_dpp v185, v185, v185 row_shr:8 row_mask:0xf bank_mask:0xf
	v_fmac_f32_dpp v191, v191, v189 row_shr:8 row_mask:0xf bank_mask:0xf
	v_mul_f32_dpp v189, v189, v189 row_shr:8 row_mask:0xf bank_mask:0xf
	v_fmac_f32_dpp v190, v190, v187 row_shr:8 row_mask:0xf bank_mask:0xf
	v_mul_f32_dpp v187, v187, v187 row_shr:8 row_mask:0xf bank_mask:0xf

; __device__ __forceinline__ void lru_fused(const bf16* XC, const bf16* Wrg_t, const bf16* PROJ, bf16* YL, const float* b_a, const float* b_x, const float* sp8,
;                                           LAS unsigned char* lds, int tid, int lane, int wave, int vcu, int G) {
;     ...
; #pragma unroll
;             for (int r2 = 0; r2 < 2; ++r2)
; #pragma unroll
;                 for (int c2 = 0; c2 < 2; ++c2)
;                     asm volatile("s_nop 1\n\t" LRU_STEP(1) LRU_STEP(2) LRU_STEP(4) LRU_STEP(8)
;                                  : "+v"(A[r2][c2][0]), "+v"(A[r2][c2][1]), "+v"(A[r2][c2][2]), "+v"(A[r2][c2][3]), "+v"(U[r2][c2][0]), "+v"(U[r2][c2][1]), "+v"(U[r2][c2][2]), "+v"(U[r2][c2][3]));
	s_nop 1
	v_fmac_f32_dpp v94, v94, v98 row_shr:1 row_mask:0xf bank_mask:0xf
	v_mul_f32_dpp v98, v98, v98 row_shr:1 row_mask:0xf bank_mask:0xf
	v_fmac_f32_dpp v95, v95, v99 row_shr:1 row_mask:0xf bank_mask:0xf
	v_mul_f32_dpp v99, v99, v99 row_shr:1 row_mask:0xf bank_mask:0xf
	v_fmac_f32_dpp v96, v96, v100 row_shr:1 row_mask:0xf bank_mask:0xf
	v_mul_f32_dpp v100, v100, v100 row_shr:1 row_mask:0xf bank_mask:0xf
	v_fmac_f32_dpp v97, v97, v101 row_shr:1 row_mask:0xf bank_mask:0xf
	v_mul_f32_dpp v101, v101, v101 row_shr:1 row_mask:0xf bank_mask:0xf
	v_fmac_f32_dpp v94, v94, v98 row_shr:2 row_mask:0xf bank_mask:0xf
	v_mul_f32_dpp v98, v98, v98 row_shr:2 row_mask:0xf bank_mask:0xf
	v_fmac_f32_dpp v95, v95, v99 row_shr:2 row_mask:0xf bank_mask:0xf
	v_mul_f32_dpp v99, v99, v99 row_shr:2 row_mask:0xf bank_mask:0xf
	v_fmac_f32_dpp v96, v96, v100 row_shr:2 row_mask:0xf bank_mask:0xf
	v_mul_f32_dpp v100, v100, v100 row_shr:2 row_mask:0xf bank_mask:0xf
	v_fmac_f32_dpp v97, v97, v101 row_shr:2 row_mask:0xf bank_mask:0xf
	v_mul_f32_dpp v101, v101, v101 row_shr:2 row_mask:0xf bank_mask:0xf
	v_fmac_f32_dpp v94, v94, v98 row_shr:4 row_mask:0xf bank_mask:0xf
	v_mul_f32_dpp v98, v98, v98 row_shr:4 row_mask:0xf bank_mask:0xf
	v_fmac_f32_dpp v95, v95, v99 row_shr:4 row_mask:0xf bank_mask:0xf
	v_mul_f32_dpp v99, v99, v99 row_shr:4 row_mask:0xf bank_mask:0xf
	v_fmac_f32_dpp v96, v96, v100 row_shr:4 row_mask:0xf bank_mask:0xf
	v_mul_f32_dpp v100, v100, v100 row_shr:4 row_mask:0xf bank_mask:0xf
	v_fmac_f32_dpp v97, v97, v101 row_shr:4 row_mask:0xf bank_mask:0xf
	v_mul_f32_dpp v101, v101, v101 row_shr:4 row_mask:0xf bank_mask:0xf
	v_fmac_f32_dpp v94, v94, v98 row_shr:8 row_mask:0xf bank_mask:0xf
	v_mul_f32_dpp v98, v98, v98 row_shr:8 row_mask:0xf bank_mask:0xf
	v_fmac_f32_dpp v95, v95, v99 row_shr:8 row_mask:0xf bank_mask:0xf
	v_mul_f32_dpp v99, v99, v99 row_shr:8 row_mask:0xf bank_mask:0xf
	v_fmac_f32_dpp v96, v96, v100 row_shr:8 row_mask:0xf bank_mask:0xf
	v_mul_f32_dpp v100, v100, v100 row_shr:8 row_mask:0xf bank_mask:0xf
	v_fmac_f32_dpp v97, v97, v101 row_shr:8 row_mask:0xf bank_mask:0xf
	v_mul_f32_dpp v101, v101, v101 row_shr:8 row_mask:0xf bank_mask:0xf

; __device__ __forceinline__ void lru_fused(const bf16* XC, const bf16* Wrg_t, const bf16* PROJ, bf16* YL, const float* b_a, const float* b_x, const float* sp8,
;                                           LAS unsigned char* lds, int tid, int lane, int wave, int vcu, int G) {
;     ...
;             for (int r2 = 0; r2 < 2; ++r2)
; #pragma unroll
;                 for (int c2 = 0; c2 < 2; ++c2)
;                     asm volatile("s_nop 1\n\t" LRU_STEP(1) LRU_STEP(2) LRU_STEP(4) LRU_STEP(8)
;                                  : "+v"(A[r2][c2][0]), "+v"(A[r2][c2][1]), "+v"(A[r2][c2][2]), "+v"(A[r2][c2][3]), "+v"(U[r2][c2][0]), "+v"(U[r2][c2][1]), "+v"(U[r2][c2][2]), "+v"(U[r2][c2][3]));
;     ...
;             const int l15 = (lane & 48) | 15;
; #pragma unroll
;             for (int c2 = 0; c2 < 2; ++c2)
; #pragma unroll
;                 for (int j = 0; j < 4; ++j) { const float a15 = __shfl(A[0][c2][j], l15), u15 = __shfl(U[0][c2][j], l15);
;                     U[1][c2][j] = A[1][c2][j] * u15 + U[1][c2][j]; A[1][c2][j] = A[1][c2][j] * a15; }
	ds_bpermute_b32 v106, v172, v189
	s_waitcnt lgkmcnt(4)
	v_pk_fma_f32 v[94:95], v[98:99], v[102:103], v[94:95]
	s_waitcnt lgkmcnt(3)
	v_pk_mul_f32 v[98:99], v[98:99], v[90:91]
	ds_bpermute_b32 v90, v172, v181
	ds_bpermute_b32 v91, v172, v176
	s_waitcnt lgkmcnt(3)
	v_pk_fma_f32 v[96:97], v[100:101], v[104:105], v[96:97]
	ds_bpermute_b32 v102, v172, v183
	ds_bpermute_b32 v104, v172, v186
	ds_bpermute_b32 v103, v172, v185
	ds_bpermute_b32 v105, v172, v188
	ds_bpermute_b32 v108, v172, v191
	ds_bpermute_b32 v109, v172, v190
	ds_bpermute_b32 v107, v172, v187
	s_and_b32 s24, s22, 1
	s_nop 1
	v_fmac_f32_dpp v86, v86, v4 row_shr:1 row_mask:0xf bank_mask:0xf
	v_mul_f32_dpp v4, v4, v4 row_shr:1 row_mask:0xf bank_mask:0xf
	v_fmac_f32_dpp v87, v87, v5 row_shr:1 row_mask:0xf bank_mask:0xf
	v_mul_f32_dpp v5, v5, v5 row_shr:1 row_mask:0xf bank_mask:0xf
	v_fmac_f32_dpp v88, v88, v92 row_shr:1 row_mask:0xf bank_mask:0xf
	v_mul_f32_dpp v92, v92, v92 row_shr:1 row_mask:0xf bank_mask:0xf
	v_fmac_f32_dpp v89, v89, v93 row_shr:1 row_mask:0xf bank_mask:0xf
	v_mul_f32_dpp v93, v93, v93 row_shr:1 row_mask:0xf bank_mask:0xf
	v_fmac_f32_dpp v86, v86, v4 row_shr:2 row_mask:0xf bank_mask:0xf
	v_mul_f32_dpp v4, v4, v4 row_shr:2 row_mask:0xf bank_mask:0xf
	v_fmac_f32_dpp v87, v87, v5 row_shr:2 row_mask:0xf bank_mask:0xf
	v_mul_f32_dpp v5, v5, v5 row_shr:2 row_mask:0xf bank_mask:0xf
	v_fmac_f32_dpp v88, v88, v92 row_shr:2 row_mask:0xf bank_mask:0xf
	v_mul_f32_dpp v92, v92, v92 row_shr:2 row_mask:0xf bank_mask:0xf
	v_fmac_f32_dpp v89, v89, v93 row_shr:2 row_mask:0xf bank_mask:0xf
	v_mul_f32_dpp v93, v93, v93 row_shr:2 row_mask:0xf bank_mask:0xf
	v_fmac_f32_dpp v86, v86, v4 row_shr:4 row_mask:0xf bank_mask:0xf
	v_mul_f32_dpp v4, v4, v4 row_shr:4 row_mask:0xf bank_mask:0xf
	v_fmac_f32_dpp v87, v87, v5 row_shr:4 row_mask:0xf bank_mask:0xf
	v_mul_f32_dpp v5, v5, v5 row_shr:4 row_mask:0xf bank_mask:0xf
	v_fmac_f32_dpp v88, v88, v92 row_shr:4 row_mask:0xf bank_mask:0xf
	v_mul_f32_dpp v92, v92, v92 row_shr:4 row_mask:0xf bank_mask:0xf
	v_fmac_f32_dpp v89, v89, v93 row_shr:4 row_mask:0xf bank_mask:0xf
	v_mul_f32_dpp v93, v93, v93 row_shr:4 row_mask:0xf bank_mask:0xf
	v_fmac_f32_dpp v86, v86, v4 row_shr:8 row_mask:0xf bank_mask:0xf
	v_mul_f32_dpp v4, v4, v4 row_shr:8 row_mask:0xf bank_mask:0xf
	v_fmac_f32_dpp v87, v87, v5 row_shr:8 row_mask:0xf bank_mask:0xf
	v_mul_f32_dpp v5, v5, v5 row_shr:8 row_mask:0xf bank_mask:0xf
	v_fmac_f32_dpp v88, v88, v92 row_shr:8 row_mask:0xf bank_mask:0xf
	v_mul_f32_dpp v92, v92, v92 row_shr:8 row_mask:0xf bank_mask:0xf
	v_fmac_f32_dpp v89, v89, v93 row_shr:8 row_mask:0xf bank_mask:0xf
	v_mul_f32_dpp v93, v93, v93 row_shr:8 row_mask:0xf bank_mask:0xf

; #define LAS __attribute__((address_space(3)))
; __device__ __forceinline__ void lru_fused(const bf16* XC, const bf16* Wrg_t, const bf16* PROJ, bf16* YL, const float* b_a, const float* b_x, const float* sp8,
;                                           LAS unsigned char* lds, int tid, int lane, int wave, int vcu, int G) {
;     ...
;             const int l15 = (lane & 48) | 15;
; #pragma unroll
;             for (int c2 = 0; c2 < 2; ++c2)
; #pragma unroll
;                 for (int j = 0; j < 4; ++j) { const float a15 = __shfl(A[0][c2][j], l15), u15 = __shfl(U[0][c2][j], l15);
;                     U[1][c2][j] = A[1][c2][j] * u15 + U[1][c2][j]; A[1][c2][j] = A[1][c2][j] * a15; }
;             LAS float* xp = xch + (i & 1) * 512;
;             if (fr == 15) {
; #pragma unroll
;                 for (int c2 = 0; c2 < 2; ++c2) { *(LAS f32x4*)(xp + wave * 32 + 16 * c2 + 4 * fq) = (f32x4){A[1][c2][0], A[1][c2][1], A[1][c2][2], A[1][c2][3]};
;                     *(LAS f32x4*)(xp + 256 + wave * 32 + 16 * c2 + 4 * fq) = (f32x4){U[1][c2][0], U[1][c2][1], U[1][c2][2], U[1][c2][3]}; } }
	s_lshl_b32 s23, s24, 11
	s_waitcnt lgkmcnt(7)
	v_pk_mul_f32 v[100:101], v[100:101], v[90:91]
	s_waitcnt lgkmcnt(3)
	v_pk_fma_f32 v[86:87], v[4:5], v[104:105], v[86:87]
	v_pk_mul_f32 v[90:91], v[4:5], v[102:103]
	s_waitcnt lgkmcnt(1)
	v_pk_fma_f32 v[88:89], v[92:93], v[108:109], v[88:89]
	s_waitcnt lgkmcnt(0)
	v_pk_mul_f32 v[92:93], v[92:93], v[106:107]
	s_add_i32 s23, s23, 0
	s_and_saveexec_b64 s[66:67], s[2:3]
	s_cbranch_execz .LBB0_458
	s_lshl_b32 s25, s6, 2
	s_add_i32 s25, s23, s25
	v_lshl_add_u32 v3, v165, 2, s25
	ds_write_b128 v3, v[98:101] offset:36864
	ds_write_b128 v3, v[94:97] offset:37888
	ds_write_b128 v3, v[90:93] offset:36928
	ds_write_b128 v3, v[86:89] offset:37952
